# norm phases: skip the context fold loads of a past-the-end (dummy) second row; on top of K-tile stride 224
# baseline (speedup 1.0000x reference)
.LBB0_114:
	s_or_b64 exec, exec, s[2:3]
	v_add_u32_e32 v134, s9, v121
	v_readlane_b32 s2, v255, 9
	s_nop 1
	v_cmp_gt_i32_e64 s[40:41], s2, v134
	s_nop 1
	v_cndmask_b32_e64 v40, v121, v134, s[40:41]
	v_cmp_lt_i32_e32 vcc, s90, v40
	v_add_u32_e32 v34, 0xffff8000, v40
	s_and_saveexec_b64 s[2:3], vcc
	s_xor_b64 s[2:3], exec, s[2:3]
	v_mov_b32_e32 v35, v157
	v_lshlrev_b64 v[42:43], 12, v[34:35]
	v_lshl_add_u64 v[48:49], s[26:27], 0, v[42:43]
	s_andn2_saveexec_b64 s[2:3], s[2:3]
	v_ashrrev_i32_e32 v41, 31, v40
	v_lshlrev_b64 v[42:43], 12, v[40:41]
	v_mov_b32_e32 v35, v157
	v_lshl_add_u64 v[48:49], s[48:49], 0, v[42:43]
	v_lshlrev_b64 v[42:43], 12, v[34:35]
	s_or_b64 exec, exec, s[2:3]
	v_min_i32_e32 v33, 0x8000, v40
	v_ashrrev_i32_e32 v33, 12, v33
	v_mul_hi_i32_i24_e32 v35, 0x9000, v33
	v_mul_i32_i24_e32 v34, 0x9000, v33
	v_lshl_add_u64 v[34:35], s[56:57], 0, v[34:35]
	v_lshl_add_u64 v[34:35], v[34:35], 0, v[156:157]
	v_mov_b32_e32 v33, v157
	s_waitcnt vmcnt(16)
	v_lshl_add_u64 v[76:77], v[48:49], 0, v[32:33]
	v_add_co_u32_e32 v32, vcc, 0x7000, v34
	global_load_dwordx4 v[84:87], v[76:77], off
	s_nop 0
	v_addc_co_u32_e32 v33, vcc, 0, v35, vcc
	v_add_co_u32_e32 v52, vcc, 0x6000, v34
	v_cmp_lt_i32_e64 s[42:43], s90, v40
	s_nop 0
	s_and_b64 s[42:43], s[42:43], s[40:41]
	s_nop 0
	v_addc_co_u32_e32 v53, vcc, 0, v35, vcc
	global_load_dwordx4 v[48:51], v[32:33], off
	s_nop 0
	global_load_dwordx4 v[52:55], v[52:53], off
	v_lshl_add_u64 v[118:119], v[124:125], 0, v[42:43]
	v_mov_b32_e32 v138, 0
	v_mov_b32_e32 v142, 0
	v_mov_b32_e32 v143, 0
	v_mov_b32_e32 v144, 0
	v_mov_b32_e32 v145, 0
	s_and_saveexec_b64 s[2:3], s[42:43]
	s_cbranch_execz .LBB0_120
	v_add_co_u32_e32 v246, vcc, 0x800000, v118
	s_nop 1
	v_addc_co_u32_e32 v247, vcc, 0, v119, vcc
	v_add_co_u32_e32 v248, vcc, 0x1000000, v118
	s_nop 1
	v_addc_co_u32_e32 v249, vcc, 0, v119, vcc
	v_add_co_u32_e32 v250, vcc, 0x1800000, v118
	s_nop 1
	v_addc_co_u32_e32 v251, vcc, 0, v119, vcc
	global_load_dwordx4 v[214:217], v[118:119], off
	global_load_dwordx4 v[218:221], v[246:247], off
	global_load_dwordx4 v[222:225], v[248:249], off
	global_load_dwordx4 v[226:229], v[250:251], off
	global_load_dwordx4 v[230:233], v[118:119], off offset:1024
	global_load_dwordx4 v[234:237], v[246:247], off offset:1024
	global_load_dwordx4 v[238:241], v[248:249], off offset:1024
	global_load_dwordx4 v[242:245], v[250:251], off offset:1024
	s_waitcnt vmcnt(0)
	v_pk_add_f32 v[214:215], v[214:215], v[218:219]
	v_pk_add_f32 v[216:217], v[216:217], v[220:221]
	v_pk_add_f32 v[224:225], v[224:225], v[228:229]
	v_pk_add_f32 v[222:223], v[222:223], v[226:227]
	v_pk_add_f32 v[144:145], v[216:217], v[224:225]
	v_pk_add_f32 v[142:143], v[214:215], v[222:223]

.LBB0_454:
	s_or_b64 exec, exec, s[2:3]
	v_add_u32_e32 v134, s9, v121
	v_cmp_gt_i32_e64 s[40:41], s77, v134
	s_nop 1
	v_cndmask_b32_e64 v36, v121, v134, s[40:41]
	v_cmp_lt_i32_e32 vcc, s90, v36
	v_add_u32_e32 v34, 0xffff8000, v36
	s_and_saveexec_b64 s[2:3], vcc
	s_xor_b64 s[2:3], exec, s[2:3]
	v_mov_b32_e32 v35, v157
	v_lshlrev_b64 v[38:39], 12, v[34:35]
	v_lshl_add_u64 v[48:49], s[26:27], 0, v[38:39]
	s_andn2_saveexec_b64 s[2:3], s[2:3]
	v_ashrrev_i32_e32 v37, 31, v36
	v_lshlrev_b64 v[38:39], 12, v[36:37]
	v_mov_b32_e32 v35, v157
	v_lshl_add_u64 v[48:49], s[44:45], 0, v[38:39]
	v_lshlrev_b64 v[38:39], 12, v[34:35]
	s_or_b64 exec, exec, s[2:3]
	v_min_i32_e32 v33, 0x8000, v36
	v_ashrrev_i32_e32 v33, 12, v33
	v_mul_hi_i32_i24_e32 v35, 0x9000, v33
	v_mul_i32_i24_e32 v34, 0x9000, v33
	v_lshl_add_u64 v[34:35], s[56:57], 0, v[34:35]
	v_lshl_add_u64 v[34:35], v[34:35], 0, v[156:157]
	v_mov_b32_e32 v33, v157
	v_lshl_add_u64 v[76:77], v[48:49], 0, v[32:33]
	v_add_co_u32_e32 v32, vcc, 0x4000, v34
	global_load_dwordx4 v[84:87], v[76:77], off
	s_nop 0
	v_addc_co_u32_e32 v33, vcc, 0, v35, vcc
	v_add_co_u32_e32 v52, vcc, 0x3000, v34
	v_cmp_lt_i32_e64 s[42:43], s90, v36
	s_nop 0
	s_and_b64 s[42:43], s[42:43], s[40:41]
	s_nop 0
	v_addc_co_u32_e32 v53, vcc, 0, v35, vcc
	global_load_dwordx4 v[48:51], v[32:33], off
	s_nop 0
	global_load_dwordx4 v[52:55], v[52:53], off
	v_lshl_add_u64 v[118:119], v[124:125], 0, v[38:39]
	v_mov_b32_e32 v138, 0
	v_mov_b32_e32 v142, 0
	v_mov_b32_e32 v143, 0
	v_mov_b32_e32 v144, 0
	v_mov_b32_e32 v145, 0
	s_and_saveexec_b64 s[2:3], s[42:43]
	s_cbranch_execz .LBB0_460
	v_add_co_u32_e32 v246, vcc, 0x800000, v118
	s_nop 1
	v_addc_co_u32_e32 v247, vcc, 0, v119, vcc
	v_add_co_u32_e32 v248, vcc, 0x1000000, v118
	s_nop 1
	v_addc_co_u32_e32 v249, vcc, 0, v119, vcc
	v_add_co_u32_e32 v250, vcc, 0x1800000, v118
	s_nop 1
	v_addc_co_u32_e32 v251, vcc, 0, v119, vcc
	global_load_dwordx4 v[214:217], v[118:119], off
	global_load_dwordx4 v[218:221], v[246:247], off
	global_load_dwordx4 v[222:225], v[248:249], off
	global_load_dwordx4 v[226:229], v[250:251], off
	global_load_dwordx4 v[230:233], v[118:119], off offset:1024
	global_load_dwordx4 v[234:237], v[246:247], off offset:1024
	global_load_dwordx4 v[238:241], v[248:249], off offset:1024
	global_load_dwordx4 v[242:245], v[250:251], off offset:1024
	s_waitcnt vmcnt(0)
	v_pk_add_f32 v[214:215], v[214:215], v[218:219]
	v_pk_add_f32 v[216:217], v[216:217], v[220:221]
	v_pk_add_f32 v[224:225], v[224:225], v[228:229]
	v_pk_add_f32 v[222:223], v[222:223], v[226:227]
	v_pk_add_f32 v[144:145], v[216:217], v[224:225]
	v_pk_add_f32 v[142:143], v[214:215], v[222:223]

.LBB0_580:
	s_or_b64 exec, exec, s[2:3]
	v_add_u32_e32 v134, s9, v121
	v_cmp_gt_i32_e64 s[38:39], s77, v134
	s_nop 1
	v_cndmask_b32_e64 v18, v121, v134, s[38:39]
	v_cmp_lt_i32_e32 vcc, s90, v18
	v_add_u32_e32 v36, 0xffff8000, v18
	s_and_saveexec_b64 s[2:3], vcc
	s_xor_b64 s[2:3], exec, s[2:3]
	v_mov_b32_e32 v37, v157
	v_lshlrev_b64 v[20:21], 12, v[36:37]
	v_lshl_add_u64 v[22:23], s[30:31], 0, v[20:21]
	s_andn2_saveexec_b64 s[2:3], s[2:3]
	v_ashrrev_i32_e32 v19, 31, v18
	v_lshlrev_b64 v[20:21], 12, v[18:19]
	v_mov_b32_e32 v37, v157
	v_lshl_add_u64 v[22:23], s[36:37], 0, v[20:21]
	v_lshlrev_b64 v[20:21], 12, v[36:37]
	s_or_b64 exec, exec, s[2:3]
	v_min_i32_e32 v17, 0x8000, v18
	v_ashrrev_i32_e32 v17, 12, v17
	v_mul_hi_i32_i24_e32 v37, 0x9000, v17
	v_mul_i32_i24_e32 v36, 0x9000, v17
	v_lshl_add_u64 v[36:37], s[56:57], 0, v[36:37]
	v_lshl_add_u64 v[72:73], v[36:37], 0, v[156:157]
	v_mov_b32_e32 v17, v157
	v_lshl_add_u64 v[74:75], v[22:23], 0, v[16:17]
	v_add_co_u32_e32 v16, vcc, 0x1000, v72
	global_load_dwordx4 v[80:83], v[74:75], off
	s_nop 0
	v_addc_co_u32_e32 v17, vcc, 0, v73, vcc
	global_load_dwordx4 v[48:51], v[16:17], off
	global_load_dwordx4 v[40:43], v[72:73], off
	v_cmp_lt_i32_e32 vcc, s90, v18
	s_and_b64 s[6:7], s[44:45], vcc
	s_and_b64 s[6:7], s[6:7], s[38:39]
	v_lshl_add_u64 v[118:119], v[124:125], 0, v[20:21]
	v_mov_b32_e32 v142, 0
	v_mov_b32_e32 v138, 0
	v_mov_b32_e32 v139, 0
	v_mov_b32_e32 v140, 0
	v_mov_b32_e32 v141, 0
	s_and_saveexec_b64 s[2:3], s[6:7]
	s_cbranch_execz .LBB0_586
	v_add_co_u32_e32 v246, vcc, 0x800000, v118
	s_nop 1
	v_addc_co_u32_e32 v247, vcc, 0, v119, vcc
	v_add_co_u32_e32 v248, vcc, 0x1000000, v118
	s_nop 1
	v_addc_co_u32_e32 v249, vcc, 0, v119, vcc
	v_add_co_u32_e32 v250, vcc, 0x1800000, v118
	s_nop 1
	v_addc_co_u32_e32 v251, vcc, 0, v119, vcc
	global_load_dwordx4 v[214:217], v[118:119], off
	global_load_dwordx4 v[218:221], v[246:247], off
	global_load_dwordx4 v[222:225], v[248:249], off
	global_load_dwordx4 v[226:229], v[250:251], off
	global_load_dwordx4 v[230:233], v[118:119], off offset:1024
	global_load_dwordx4 v[234:237], v[246:247], off offset:1024
	global_load_dwordx4 v[238:241], v[248:249], off offset:1024
	global_load_dwordx4 v[242:245], v[250:251], off offset:1024
	s_waitcnt vmcnt(0)
	v_pk_add_f32 v[214:215], v[214:215], v[218:219]
	v_pk_add_f32 v[216:217], v[216:217], v[220:221]
	v_pk_add_f32 v[224:225], v[224:225], v[228:229]
	v_pk_add_f32 v[222:223], v[222:223], v[226:227]
	v_pk_add_f32 v[140:141], v[216:217], v[224:225]
	v_pk_add_f32 v[138:139], v[214:215], v[222:223]
